# residual epilogue: prefetched quads consumed in place (24 register copies removed)
# baseline (speedup 1.0000x reference)
.LBB0_860:
	s_or_b64 exec, exec, s[44:45]
	v_or_b32_e32 v112, 16, v140
	s_waitcnt lgkmcnt(0)
	v_ashrrev_i32_e32 v113, 31, v112
	v_lshlrev_b64 v[116:117], 11, v[112:113]
	v_lshl_add_u64 v[116:117], s[80:81], 0, v[116:117]
	v_lshl_add_u64 v[120:121], v[138:139], 1, v[116:117]
	s_waitcnt vmcnt(16)
	v_lshlrev_b32_e32 v122, 16, v160
	v_and_b32_e32 v116, 0xffff0000, v160
	v_lshlrev_b32_e32 v123, 16, v161
	v_and_b32_e32 v117, 0xffff0000, v161
	v_lshlrev_b32_e32 v124, 16, v162
	v_and_b32_e32 v118, 0xffff0000, v162
	v_lshlrev_b32_e32 v125, 16, v163
	v_and_b32_e32 v119, 0xffff0000, v163
	v_fmac_f32_e32 v122, s2, v108
	v_fmac_f32_e32 v116, s2, v109
	v_fmac_f32_e32 v123, s2, v110
	v_fmac_f32_e32 v117, s2, v111
	v_fmac_f32_e32 v124, s2, v104
	v_fmac_f32_e32 v118, s2, v105
	v_fmac_f32_e32 v125, s2, v106
	v_fmac_f32_e32 v119, s2, v107
	v_cvt_pk_bf16_f32 v104, v122, v116
	v_cvt_pk_bf16_f32 v105, v123, v117
	v_cvt_pk_bf16_f32 v106, v124, v118
	v_cvt_pk_bf16_f32 v107, v125, v119
	v_and_b32_e32 v117, 0xffff0000, v104
	v_and_b32_e32 v119, 0xffff0000, v105
	v_lshlrev_b32_e32 v116, 16, v104
	v_lshlrev_b32_e32 v118, 16, v105
	v_and_b32_e32 v123, 0xffff0000, v106
	global_store_dwordx4 v[120:121], v[104:107], off
	v_lshlrev_b32_e32 v122, 16, v106
	v_and_b32_e32 v125, 0xffff0000, v107
	v_mul_f32_e32 v104, v117, v117
	v_mul_f32_e32 v105, v119, v119
	v_mul_f32_e32 v106, v123, v123
	v_fmac_f32_e32 v104, v116, v116
	v_fmac_f32_e32 v105, v118, v118
	v_lshlrev_b32_e32 v124, 16, v107
	v_mul_f32_e32 v107, v125, v125
	v_fmac_f32_e32 v106, v122, v122
	v_add_f32_e32 v104, v104, v105
	v_fmac_f32_e32 v107, v124, v124
	v_add_f32_e32 v104, v104, v106
	v_add_f32_e32 v104, v104, v107
	s_waitcnt vmcnt(16)
	v_lshlrev_b32_e32 v105, 16, v164
	v_and_b32_e32 v106, 0xffff0000, v164
	v_lshlrev_b32_e32 v107, 16, v165
	v_and_b32_e32 v108, 0xffff0000, v165
	v_lshlrev_b32_e32 v109, 16, v166
	v_and_b32_e32 v110, 0xffff0000, v166
	v_lshlrev_b32_e32 v116, 16, v167
	v_and_b32_e32 v111, 0xffff0000, v167
	v_fmac_f32_e32 v105, s2, v100
	v_fmac_f32_e32 v106, s2, v101
	v_fmac_f32_e32 v110, s2, v97
	v_fmac_f32_e32 v116, s2, v98
	v_cvt_pk_bf16_f32 v98, v105, v106
	v_fmac_f32_e32 v107, s2, v102
	v_and_b32_e32 v97, 0xffff0000, v98
	v_fmac_f32_e32 v108, s2, v103
	v_fmac_f32_e32 v109, s2, v96
	v_fmac_f32_e32 v111, s2, v99
	v_cvt_pk_bf16_f32 v99, v107, v108
	v_lshlrev_b32_e32 v96, 16, v98
	v_and_b32_e32 v103, 0xffff0000, v99
	v_mul_f32_e32 v97, v97, v97
	v_cvt_pk_bf16_f32 v100, v109, v110
	v_lshlrev_b32_e32 v102, 16, v99
	v_and_b32_e32 v106, 0xffff0000, v100
	v_mul_f32_e32 v103, v103, v103
	v_fmac_f32_e32 v97, v96, v96
	v_cvt_pk_bf16_f32 v101, v116, v111
	v_lshlrev_b32_e32 v105, 16, v100
	v_and_b32_e32 v108, 0xffff0000, v101
	v_mul_f32_e32 v106, v106, v106
	v_fmac_f32_e32 v103, v102, v102
	v_add_f32_e32 v96, v104, v97
	v_lshlrev_b32_e32 v107, 16, v101
	v_mul_f32_e32 v108, v108, v108
	v_fmac_f32_e32 v106, v105, v105
	v_add_f32_e32 v96, v96, v103
	v_add_f32_e32 v96, v96, v106
	v_fmac_f32_e32 v108, v107, v107
	v_add_f32_e32 v96, v96, v108
	v_mov_b32_e32 v97, v96
	s_nop 1
	v_permlane16_swap_b32_e32 v96, v97
	global_store_dwordx4 v[120:121], v[98:101], off offset:256
	s_waitcnt lgkmcnt(0)
	v_add_f32_e32 v96, v96, v97
	v_mov_b32_e32 v97, v96
	s_nop 1
	v_permlane32_swap_b32_e32 v96, v97
	s_and_saveexec_b64 s[44:45], s[40:41]
	s_cbranch_execz .LBB0_862
	v_lshlrev_b64 v[98:99], 6, v[112:113]
	v_lshl_add_u64 v[98:99], s[20:21], 0, v[98:99]
	v_lshl_add_u64 v[98:99], s[34:35], 2, v[98:99]
	s_lshl_b32 s36, s27, 2
	v_lshl_add_u64 v[98:99], v[98:99], 0, s[36:37]
	s_waitcnt lgkmcnt(0)
	v_add_f32_e32 v96, v96, v97
	global_store_dword v[98:99], v96, off
.LBB0_862:
	s_or_b64 exec, exec, s[44:45]
	v_or_b32_e32 v96, 32, v140
	s_waitcnt lgkmcnt(0)
	v_ashrrev_i32_e32 v97, 31, v96
	v_lshlrev_b64 v[98:99], 11, v[96:97]
	v_lshl_add_u64 v[98:99], s[80:81], 0, v[98:99]
	v_lshl_add_u64 v[102:103], v[138:139], 1, v[98:99]
	s_waitcnt vmcnt(17)
	v_lshlrev_b32_e32 v104, 16, v168
	v_and_b32_e32 v98, 0xffff0000, v168
	v_lshlrev_b32_e32 v105, 16, v169
	v_and_b32_e32 v99, 0xffff0000, v169
	v_lshlrev_b32_e32 v106, 16, v170
	v_and_b32_e32 v100, 0xffff0000, v170
	v_lshlrev_b32_e32 v107, 16, v171
	v_and_b32_e32 v101, 0xffff0000, v171
	v_fmac_f32_e32 v104, s2, v92
	v_fmac_f32_e32 v98, s2, v93
	v_fmac_f32_e32 v105, s2, v94
	v_fmac_f32_e32 v99, s2, v95
	v_fmac_f32_e32 v106, s2, v88
	v_fmac_f32_e32 v100, s2, v89
	v_fmac_f32_e32 v107, s2, v90
	v_fmac_f32_e32 v101, s2, v91
	v_cvt_pk_bf16_f32 v88, v104, v98
	v_cvt_pk_bf16_f32 v89, v105, v99
	v_cvt_pk_bf16_f32 v90, v106, v100
	v_cvt_pk_bf16_f32 v91, v107, v101
	v_and_b32_e32 v99, 0xffff0000, v88
	v_and_b32_e32 v101, 0xffff0000, v89
	v_lshlrev_b32_e32 v98, 16, v88
	v_lshlrev_b32_e32 v100, 16, v89
	v_and_b32_e32 v105, 0xffff0000, v90
	global_store_dwordx4 v[102:103], v[88:91], off
	v_lshlrev_b32_e32 v104, 16, v90
	v_and_b32_e32 v107, 0xffff0000, v91
	v_mul_f32_e32 v88, v99, v99
	v_mul_f32_e32 v89, v101, v101
	v_mul_f32_e32 v90, v105, v105
	v_fmac_f32_e32 v88, v98, v98
	v_fmac_f32_e32 v89, v100, v100
	v_lshlrev_b32_e32 v106, 16, v91
	v_mul_f32_e32 v91, v107, v107
	v_fmac_f32_e32 v90, v104, v104
	v_add_f32_e32 v88, v88, v89
	v_fmac_f32_e32 v91, v106, v106
	v_add_f32_e32 v88, v88, v90
	v_add_f32_e32 v88, v88, v91
	s_waitcnt vmcnt(17)
	v_lshlrev_b32_e32 v89, 16, v172
	v_and_b32_e32 v90, 0xffff0000, v172
	v_lshlrev_b32_e32 v91, 16, v173
	v_and_b32_e32 v92, 0xffff0000, v173
	v_lshlrev_b32_e32 v93, 16, v174
	v_and_b32_e32 v94, 0xffff0000, v174
	v_lshlrev_b32_e32 v98, 16, v175
	v_and_b32_e32 v95, 0xffff0000, v175
	v_fmac_f32_e32 v89, s2, v84
	v_fmac_f32_e32 v90, s2, v85
	v_fmac_f32_e32 v94, s2, v81
	v_fmac_f32_e32 v98, s2, v82
	v_cvt_pk_bf16_f32 v82, v89, v90
	v_fmac_f32_e32 v91, s2, v86
	v_and_b32_e32 v81, 0xffff0000, v82
	v_fmac_f32_e32 v92, s2, v87
	v_fmac_f32_e32 v93, s2, v80
	v_fmac_f32_e32 v95, s2, v83
	v_cvt_pk_bf16_f32 v83, v91, v92
	v_lshlrev_b32_e32 v80, 16, v82
	v_and_b32_e32 v87, 0xffff0000, v83
	v_mul_f32_e32 v81, v81, v81
	v_cvt_pk_bf16_f32 v84, v93, v94
	v_lshlrev_b32_e32 v86, 16, v83
	v_and_b32_e32 v90, 0xffff0000, v84
	v_mul_f32_e32 v87, v87, v87
	v_fmac_f32_e32 v81, v80, v80
	v_cvt_pk_bf16_f32 v85, v98, v95
	v_lshlrev_b32_e32 v89, 16, v84
	v_and_b32_e32 v92, 0xffff0000, v85
	v_mul_f32_e32 v90, v90, v90
	v_fmac_f32_e32 v87, v86, v86
	v_add_f32_e32 v80, v88, v81
	v_lshlrev_b32_e32 v91, 16, v85
	v_mul_f32_e32 v92, v92, v92
	v_fmac_f32_e32 v90, v89, v89
	v_add_f32_e32 v80, v80, v87
	v_add_f32_e32 v80, v80, v90
	v_fmac_f32_e32 v92, v91, v91
	v_add_f32_e32 v80, v80, v92
	v_mov_b32_e32 v81, v80
	s_nop 1
	v_permlane16_swap_b32_e32 v80, v81
	global_store_dwordx4 v[102:103], v[82:85], off offset:256
	s_waitcnt lgkmcnt(0)
	v_add_f32_e32 v80, v80, v81
	v_mov_b32_e32 v81, v80
	s_nop 1
	v_permlane32_swap_b32_e32 v80, v81
	s_and_saveexec_b64 s[44:45], s[40:41]
	s_cbranch_execz .LBB0_864
	v_lshlrev_b64 v[82:83], 6, v[96:97]
	v_lshl_add_u64 v[82:83], s[20:21], 0, v[82:83]
	v_lshl_add_u64 v[82:83], s[34:35], 2, v[82:83]
	s_lshl_b32 s36, s27, 2
	v_lshl_add_u64 v[82:83], v[82:83], 0, s[36:37]
	s_waitcnt lgkmcnt(0)
	v_add_f32_e32 v80, v80, v81
	global_store_dword v[82:83], v80, off
.LBB0_864:
	s_or_b64 exec, exec, s[44:45]
	v_or_b32_e32 v80, 48, v140
	s_waitcnt lgkmcnt(0)
	v_ashrrev_i32_e32 v81, 31, v80
	v_lshlrev_b64 v[82:83], 11, v[80:81]
	v_lshl_add_u64 v[82:83], s[80:81], 0, v[82:83]
	v_lshl_add_u64 v[86:87], v[138:139], 1, v[82:83]
	s_waitcnt vmcnt(18)
	v_lshlrev_b32_e32 v88, 16, v176
	v_and_b32_e32 v82, 0xffff0000, v176
	v_lshlrev_b32_e32 v89, 16, v177
	v_and_b32_e32 v83, 0xffff0000, v177
	v_lshlrev_b32_e32 v90, 16, v178
	v_and_b32_e32 v84, 0xffff0000, v178
	v_lshlrev_b32_e32 v91, 16, v179
	v_and_b32_e32 v85, 0xffff0000, v179
	v_fmac_f32_e32 v88, s2, v76
	v_fmac_f32_e32 v82, s2, v77
	v_fmac_f32_e32 v89, s2, v78
	v_fmac_f32_e32 v83, s2, v79
	v_fmac_f32_e32 v90, s2, v72
	v_fmac_f32_e32 v84, s2, v73
	v_fmac_f32_e32 v91, s2, v74
	v_fmac_f32_e32 v85, s2, v75
	v_cvt_pk_bf16_f32 v72, v88, v82
	v_cvt_pk_bf16_f32 v73, v89, v83
	v_cvt_pk_bf16_f32 v74, v90, v84
	v_cvt_pk_bf16_f32 v75, v91, v85
	v_and_b32_e32 v83, 0xffff0000, v72
	v_and_b32_e32 v85, 0xffff0000, v73
	v_lshlrev_b32_e32 v82, 16, v72
	v_lshlrev_b32_e32 v84, 16, v73
	v_and_b32_e32 v89, 0xffff0000, v74
	global_store_dwordx4 v[86:87], v[72:75], off
	v_lshlrev_b32_e32 v88, 16, v74
	v_and_b32_e32 v91, 0xffff0000, v75
	v_mul_f32_e32 v72, v83, v83
	v_mul_f32_e32 v73, v85, v85
	v_mul_f32_e32 v74, v89, v89
	v_fmac_f32_e32 v72, v82, v82
	v_fmac_f32_e32 v73, v84, v84
	v_lshlrev_b32_e32 v90, 16, v75
	v_mul_f32_e32 v75, v91, v91
	v_fmac_f32_e32 v74, v88, v88
	v_add_f32_e32 v72, v72, v73
	v_fmac_f32_e32 v75, v90, v90
	v_add_f32_e32 v72, v72, v74
	v_add_f32_e32 v72, v72, v75
	s_waitcnt vmcnt(18)
	v_lshlrev_b32_e32 v73, 16, v180
	v_and_b32_e32 v74, 0xffff0000, v180
	v_lshlrev_b32_e32 v75, 16, v181
	v_and_b32_e32 v76, 0xffff0000, v181
	v_lshlrev_b32_e32 v77, 16, v182
	v_and_b32_e32 v78, 0xffff0000, v182
	v_lshlrev_b32_e32 v82, 16, v183
	v_and_b32_e32 v79, 0xffff0000, v183
	v_fmac_f32_e32 v73, s2, v68
	v_fmac_f32_e32 v74, s2, v69
	v_fmac_f32_e32 v78, s2, v65
	v_fmac_f32_e32 v82, s2, v66
	v_cvt_pk_bf16_f32 v66, v73, v74
	v_fmac_f32_e32 v75, s2, v70
	v_and_b32_e32 v65, 0xffff0000, v66
	v_fmac_f32_e32 v76, s2, v71
	v_fmac_f32_e32 v77, s2, v64
	v_fmac_f32_e32 v79, s2, v67
	v_cvt_pk_bf16_f32 v67, v75, v76
	v_lshlrev_b32_e32 v64, 16, v66
	v_and_b32_e32 v71, 0xffff0000, v67
	v_mul_f32_e32 v65, v65, v65
	v_cvt_pk_bf16_f32 v68, v77, v78
	v_lshlrev_b32_e32 v70, 16, v67
	v_and_b32_e32 v74, 0xffff0000, v68
	v_mul_f32_e32 v71, v71, v71
	v_fmac_f32_e32 v65, v64, v64
	v_cvt_pk_bf16_f32 v69, v82, v79
	v_lshlrev_b32_e32 v73, 16, v68
	v_and_b32_e32 v76, 0xffff0000, v69
	v_mul_f32_e32 v74, v74, v74
	v_fmac_f32_e32 v71, v70, v70
	v_add_f32_e32 v64, v72, v65
	v_lshlrev_b32_e32 v75, 16, v69
	v_mul_f32_e32 v76, v76, v76
	v_fmac_f32_e32 v74, v73, v73
	v_add_f32_e32 v64, v64, v71
	v_add_f32_e32 v64, v64, v74
	v_fmac_f32_e32 v76, v75, v75
	v_add_f32_e32 v64, v64, v76
	v_mov_b32_e32 v65, v64
	s_nop 1
	v_permlane16_swap_b32_e32 v64, v65
	global_store_dwordx4 v[86:87], v[66:69], off offset:256
	s_waitcnt lgkmcnt(0)
	v_add_f32_e32 v64, v64, v65
	v_mov_b32_e32 v65, v64
	s_nop 1
	v_permlane32_swap_b32_e32 v64, v65
	s_and_saveexec_b64 s[44:45], s[40:41]
	s_cbranch_execz .LBB0_866
	v_lshlrev_b64 v[66:67], 6, v[80:81]
	v_lshl_add_u64 v[66:67], s[20:21], 0, v[66:67]
	v_lshl_add_u64 v[66:67], s[34:35], 2, v[66:67]
	s_lshl_b32 s36, s27, 2
	v_lshl_add_u64 v[66:67], v[66:67], 0, s[36:37]
	s_waitcnt lgkmcnt(0)
	v_add_f32_e32 v64, v64, v65
	global_store_dword v[66:67], v64, off
.LBB0_866:
	s_or_b64 exec, exec, s[44:45]
	v_add_u32_e32 v64, 0x80, v140
	s_waitcnt lgkmcnt(0)
	v_ashrrev_i32_e32 v65, 31, v64
	v_lshlrev_b64 v[66:67], 11, v[64:65]
	v_lshl_add_u64 v[66:67], s[80:81], 0, v[66:67]
	v_lshl_add_u64 v[70:71], v[138:139], 1, v[66:67]
	s_waitcnt vmcnt(19)
	v_lshlrev_b32_e32 v72, 16, v184
	v_and_b32_e32 v66, 0xffff0000, v184
	v_lshlrev_b32_e32 v73, 16, v185
	v_and_b32_e32 v67, 0xffff0000, v185
	v_lshlrev_b32_e32 v74, 16, v186
	v_and_b32_e32 v68, 0xffff0000, v186
	v_lshlrev_b32_e32 v75, 16, v187
	v_and_b32_e32 v69, 0xffff0000, v187
	v_fmac_f32_e32 v72, s2, v60
	v_fmac_f32_e32 v66, s2, v61
	v_fmac_f32_e32 v73, s2, v62
	v_fmac_f32_e32 v67, s2, v63
	v_fmac_f32_e32 v74, s2, v56
	v_fmac_f32_e32 v68, s2, v57
	v_fmac_f32_e32 v75, s2, v58
	v_fmac_f32_e32 v69, s2, v59
	v_cvt_pk_bf16_f32 v56, v72, v66
	v_cvt_pk_bf16_f32 v57, v73, v67
	v_cvt_pk_bf16_f32 v58, v74, v68
	v_cvt_pk_bf16_f32 v59, v75, v69
	v_and_b32_e32 v67, 0xffff0000, v56
	v_and_b32_e32 v69, 0xffff0000, v57
	v_lshlrev_b32_e32 v66, 16, v56
	v_lshlrev_b32_e32 v68, 16, v57
	v_and_b32_e32 v73, 0xffff0000, v58
	global_store_dwordx4 v[70:71], v[56:59], off
	v_lshlrev_b32_e32 v72, 16, v58
	v_and_b32_e32 v75, 0xffff0000, v59
	v_mul_f32_e32 v56, v67, v67
	v_mul_f32_e32 v57, v69, v69
	v_mul_f32_e32 v58, v73, v73
	v_fmac_f32_e32 v56, v66, v66
	v_fmac_f32_e32 v57, v68, v68
	v_lshlrev_b32_e32 v74, 16, v59
	v_mul_f32_e32 v59, v75, v75
	v_fmac_f32_e32 v58, v72, v72
	v_add_f32_e32 v56, v56, v57
	v_fmac_f32_e32 v59, v74, v74
	v_add_f32_e32 v56, v56, v58
	v_add_f32_e32 v56, v56, v59
	s_waitcnt vmcnt(19)
	v_lshlrev_b32_e32 v57, 16, v188
	v_and_b32_e32 v58, 0xffff0000, v188
	v_lshlrev_b32_e32 v59, 16, v189
	v_and_b32_e32 v60, 0xffff0000, v189
	v_lshlrev_b32_e32 v61, 16, v190
	v_and_b32_e32 v62, 0xffff0000, v190
	v_lshlrev_b32_e32 v66, 16, v191
	v_and_b32_e32 v63, 0xffff0000, v191
	v_fmac_f32_e32 v57, s2, v52
	v_fmac_f32_e32 v58, s2, v53
	v_fmac_f32_e32 v62, s2, v49
	v_fmac_f32_e32 v66, s2, v50
	v_cvt_pk_bf16_f32 v50, v57, v58
	v_fmac_f32_e32 v59, s2, v54
	v_and_b32_e32 v49, 0xffff0000, v50
	v_fmac_f32_e32 v60, s2, v55
	v_fmac_f32_e32 v61, s2, v48
	v_fmac_f32_e32 v63, s2, v51
	v_cvt_pk_bf16_f32 v51, v59, v60
	v_lshlrev_b32_e32 v48, 16, v50
	v_and_b32_e32 v55, 0xffff0000, v51
	v_mul_f32_e32 v49, v49, v49
	v_cvt_pk_bf16_f32 v52, v61, v62
	v_lshlrev_b32_e32 v54, 16, v51
	v_and_b32_e32 v58, 0xffff0000, v52
	v_mul_f32_e32 v55, v55, v55
	v_fmac_f32_e32 v49, v48, v48
	v_cvt_pk_bf16_f32 v53, v66, v63
	v_lshlrev_b32_e32 v57, 16, v52
	v_and_b32_e32 v60, 0xffff0000, v53
	v_mul_f32_e32 v58, v58, v58
	v_fmac_f32_e32 v55, v54, v54
	v_add_f32_e32 v48, v56, v49
	v_lshlrev_b32_e32 v59, 16, v53
	v_mul_f32_e32 v60, v60, v60
	v_fmac_f32_e32 v58, v57, v57
	v_add_f32_e32 v48, v48, v55
	v_add_f32_e32 v48, v48, v58
	v_fmac_f32_e32 v60, v59, v59
	v_add_f32_e32 v48, v48, v60
	v_mov_b32_e32 v49, v48
	s_nop 1
	v_permlane16_swap_b32_e32 v48, v49
	global_store_dwordx4 v[70:71], v[50:53], off offset:256
	s_waitcnt lgkmcnt(0)
	v_add_f32_e32 v48, v48, v49
	v_mov_b32_e32 v49, v48
	s_nop 1
	v_permlane32_swap_b32_e32 v48, v49
	s_and_saveexec_b64 s[44:45], s[40:41]
	s_cbranch_execz .LBB0_868
	v_lshlrev_b64 v[50:51], 6, v[64:65]
	v_lshl_add_u64 v[50:51], s[20:21], 0, v[50:51]
	v_lshl_add_u64 v[50:51], s[34:35], 2, v[50:51]
	s_lshl_b32 s36, s27, 2
	v_lshl_add_u64 v[50:51], v[50:51], 0, s[36:37]
	s_waitcnt lgkmcnt(0)
	v_add_f32_e32 v48, v48, v49
	global_store_dword v[50:51], v48, off
.LBB0_868:
	s_or_b64 exec, exec, s[44:45]
	v_add_u32_e32 v48, 0x90, v140
	s_waitcnt lgkmcnt(0)
	v_ashrrev_i32_e32 v49, 31, v48
	v_lshlrev_b64 v[50:51], 11, v[48:49]
	v_lshl_add_u64 v[50:51], s[80:81], 0, v[50:51]
	v_lshl_add_u64 v[54:55], v[138:139], 1, v[50:51]
	s_waitcnt vmcnt(20)
	v_lshlrev_b32_e32 v56, 16, v192
	v_and_b32_e32 v50, 0xffff0000, v192
	v_lshlrev_b32_e32 v57, 16, v193
	v_and_b32_e32 v51, 0xffff0000, v193
	v_lshlrev_b32_e32 v58, 16, v194
	v_and_b32_e32 v52, 0xffff0000, v194
	v_lshlrev_b32_e32 v59, 16, v195
	v_and_b32_e32 v53, 0xffff0000, v195
	v_fmac_f32_e32 v56, s2, v44
	v_fmac_f32_e32 v50, s2, v45
	v_fmac_f32_e32 v57, s2, v46
	v_fmac_f32_e32 v51, s2, v47
	v_fmac_f32_e32 v58, s2, v40
	v_fmac_f32_e32 v52, s2, v41
	v_fmac_f32_e32 v59, s2, v42
	v_fmac_f32_e32 v53, s2, v43
	v_cvt_pk_bf16_f32 v40, v56, v50
	v_cvt_pk_bf16_f32 v41, v57, v51
	v_cvt_pk_bf16_f32 v42, v58, v52
	v_cvt_pk_bf16_f32 v43, v59, v53
	v_and_b32_e32 v51, 0xffff0000, v40
	v_and_b32_e32 v53, 0xffff0000, v41
	v_lshlrev_b32_e32 v50, 16, v40
	v_lshlrev_b32_e32 v52, 16, v41
	v_and_b32_e32 v57, 0xffff0000, v42
	global_store_dwordx4 v[54:55], v[40:43], off
	v_lshlrev_b32_e32 v56, 16, v42
	v_and_b32_e32 v59, 0xffff0000, v43
	v_mul_f32_e32 v40, v51, v51
	v_mul_f32_e32 v41, v53, v53
	v_mul_f32_e32 v42, v57, v57
	v_fmac_f32_e32 v40, v50, v50
	v_fmac_f32_e32 v41, v52, v52
	v_lshlrev_b32_e32 v58, 16, v43
	v_mul_f32_e32 v43, v59, v59
	v_fmac_f32_e32 v42, v56, v56
	v_add_f32_e32 v40, v40, v41
	v_fmac_f32_e32 v43, v58, v58
	v_add_f32_e32 v40, v40, v42
	v_add_f32_e32 v40, v40, v43
	s_waitcnt vmcnt(20)
	v_lshlrev_b32_e32 v41, 16, v204
	v_and_b32_e32 v42, 0xffff0000, v204
	v_lshlrev_b32_e32 v43, 16, v205
	v_and_b32_e32 v44, 0xffff0000, v205
	v_lshlrev_b32_e32 v45, 16, v206
	v_and_b32_e32 v46, 0xffff0000, v206
	v_lshlrev_b32_e32 v50, 16, v207
	v_and_b32_e32 v47, 0xffff0000, v207
	v_fmac_f32_e32 v41, s2, v36
	v_fmac_f32_e32 v42, s2, v37
	v_fmac_f32_e32 v46, s2, v33
	v_fmac_f32_e32 v50, s2, v34
	v_cvt_pk_bf16_f32 v34, v41, v42
	v_fmac_f32_e32 v43, s2, v38
	v_and_b32_e32 v33, 0xffff0000, v34
	v_fmac_f32_e32 v44, s2, v39
	v_fmac_f32_e32 v45, s2, v32
	v_fmac_f32_e32 v47, s2, v35
	v_cvt_pk_bf16_f32 v35, v43, v44
	v_lshlrev_b32_e32 v32, 16, v34
	v_and_b32_e32 v39, 0xffff0000, v35
	v_mul_f32_e32 v33, v33, v33
	v_cvt_pk_bf16_f32 v36, v45, v46
	v_lshlrev_b32_e32 v38, 16, v35
	v_and_b32_e32 v42, 0xffff0000, v36
	v_mul_f32_e32 v39, v39, v39
	v_fmac_f32_e32 v33, v32, v32
	v_cvt_pk_bf16_f32 v37, v50, v47
	v_lshlrev_b32_e32 v41, 16, v36
	v_and_b32_e32 v44, 0xffff0000, v37
	v_mul_f32_e32 v42, v42, v42
	v_fmac_f32_e32 v39, v38, v38
	v_add_f32_e32 v32, v40, v33
	v_lshlrev_b32_e32 v43, 16, v37
	v_mul_f32_e32 v44, v44, v44
	v_fmac_f32_e32 v42, v41, v41
	v_add_f32_e32 v32, v32, v39
	v_add_f32_e32 v32, v32, v42
	v_fmac_f32_e32 v44, v43, v43
	v_add_f32_e32 v32, v32, v44
	v_mov_b32_e32 v33, v32
	s_nop 1
	v_permlane16_swap_b32_e32 v32, v33
	global_store_dwordx4 v[54:55], v[34:37], off offset:256
	s_waitcnt lgkmcnt(0)
	v_add_f32_e32 v32, v32, v33
	v_mov_b32_e32 v33, v32
	s_nop 1
	v_permlane32_swap_b32_e32 v32, v33
	s_and_saveexec_b64 s[44:45], s[40:41]
	s_cbranch_execz .LBB0_870
	v_lshlrev_b64 v[34:35], 6, v[48:49]
	v_lshl_add_u64 v[34:35], s[20:21], 0, v[34:35]
	v_lshl_add_u64 v[34:35], s[34:35], 2, v[34:35]
	s_lshl_b32 s36, s27, 2
	v_lshl_add_u64 v[34:35], v[34:35], 0, s[36:37]
	s_waitcnt lgkmcnt(0)
	v_add_f32_e32 v32, v32, v33
	global_store_dword v[34:35], v32, off

.LBB0_872:
	s_or_b64 exec, exec, s[44:45]
	v_add_u32_e32 v16, 0xb0, v140
	s_waitcnt lgkmcnt(0)
	v_ashrrev_i32_e32 v17, 31, v16
	v_lshlrev_b64 v[18:19], 11, v[16:17]
	v_lshl_add_u64 v[18:19], s[80:81], 0, v[18:19]
	v_lshl_add_u64 v[22:23], v[138:139], 1, v[18:19]
	s_waitcnt vmcnt(22)
	v_lshlrev_b32_e32 v24, 16, v216
	v_and_b32_e32 v18, 0xffff0000, v216
	v_lshlrev_b32_e32 v25, 16, v217
	v_and_b32_e32 v19, 0xffff0000, v217
	v_lshlrev_b32_e32 v26, 16, v218
	v_and_b32_e32 v20, 0xffff0000, v218
	v_lshlrev_b32_e32 v27, 16, v219
	v_and_b32_e32 v21, 0xffff0000, v219
	v_fmac_f32_e32 v24, s2, v12
	v_fmac_f32_e32 v18, s2, v13
	v_fmac_f32_e32 v25, s2, v14
	v_fmac_f32_e32 v19, s2, v15
	v_fmac_f32_e32 v26, s2, v8
	v_fmac_f32_e32 v20, s2, v9
	v_fmac_f32_e32 v27, s2, v10
	v_fmac_f32_e32 v21, s2, v11
	v_cvt_pk_bf16_f32 v8, v24, v18
	v_cvt_pk_bf16_f32 v9, v25, v19
	v_cvt_pk_bf16_f32 v10, v26, v20
	v_cvt_pk_bf16_f32 v11, v27, v21
	v_and_b32_e32 v19, 0xffff0000, v8
	v_and_b32_e32 v21, 0xffff0000, v9
	v_lshlrev_b32_e32 v18, 16, v8
	v_lshlrev_b32_e32 v20, 16, v9
	v_and_b32_e32 v25, 0xffff0000, v10
	global_store_dwordx4 v[22:23], v[8:11], off
	v_lshlrev_b32_e32 v24, 16, v10
	v_and_b32_e32 v27, 0xffff0000, v11
	v_mul_f32_e32 v8, v19, v19
	v_mul_f32_e32 v9, v21, v21
	v_mul_f32_e32 v10, v25, v25
	v_fmac_f32_e32 v8, v18, v18
	v_fmac_f32_e32 v9, v20, v20
	v_lshlrev_b32_e32 v26, 16, v11
	v_mul_f32_e32 v11, v27, v27
	v_fmac_f32_e32 v10, v24, v24
	v_add_f32_e32 v8, v8, v9
	v_fmac_f32_e32 v11, v26, v26
	v_add_f32_e32 v8, v8, v10
	v_add_f32_e32 v8, v8, v11
	s_waitcnt vmcnt(22)
	v_lshlrev_b32_e32 v9, 16, v228
	v_and_b32_e32 v10, 0xffff0000, v228
	v_lshlrev_b32_e32 v11, 16, v229
	v_and_b32_e32 v12, 0xffff0000, v229
	v_lshlrev_b32_e32 v13, 16, v230
	v_and_b32_e32 v14, 0xffff0000, v230
	v_lshlrev_b32_e32 v18, 16, v231
	v_and_b32_e32 v15, 0xffff0000, v231
	v_fmac_f32_e32 v9, s2, v4
	v_fmac_f32_e32 v10, s2, v5
	v_fmac_f32_e32 v14, s2, v1
	v_fmac_f32_e32 v18, s2, v2
	v_cvt_pk_bf16_f32 v2, v9, v10
	v_fmac_f32_e32 v11, s2, v6
	v_and_b32_e32 v1, 0xffff0000, v2
	v_fmac_f32_e32 v12, s2, v7
	v_fmac_f32_e32 v13, s2, v0
	v_fmac_f32_e32 v15, s2, v3
	v_cvt_pk_bf16_f32 v3, v11, v12
	v_lshlrev_b32_e32 v0, 16, v2
	v_and_b32_e32 v7, 0xffff0000, v3
	v_mul_f32_e32 v1, v1, v1
	v_cvt_pk_bf16_f32 v4, v13, v14
	v_lshlrev_b32_e32 v6, 16, v3
	v_and_b32_e32 v10, 0xffff0000, v4
	v_mul_f32_e32 v7, v7, v7
	v_fmac_f32_e32 v1, v0, v0
	v_cvt_pk_bf16_f32 v5, v18, v15
	v_lshlrev_b32_e32 v9, 16, v4
	v_and_b32_e32 v12, 0xffff0000, v5
	v_mul_f32_e32 v10, v10, v10
	v_fmac_f32_e32 v7, v6, v6
	v_add_f32_e32 v0, v8, v1
	v_lshlrev_b32_e32 v11, 16, v5
	v_mul_f32_e32 v12, v12, v12
	v_fmac_f32_e32 v10, v9, v9
	v_add_f32_e32 v0, v0, v7
	v_add_f32_e32 v0, v0, v10
	v_fmac_f32_e32 v12, v11, v11
	v_add_f32_e32 v0, v0, v12
	v_mov_b32_e32 v1, v0
	s_nop 1
	v_permlane16_swap_b32_e32 v0, v1
	global_store_dwordx4 v[22:23], v[2:5], off offset:256
	s_waitcnt lgkmcnt(0)
	v_add_f32_e32 v0, v0, v1
	v_mov_b32_e32 v1, v0
	s_nop 1
	v_permlane32_swap_b32_e32 v0, v1
	s_and_saveexec_b64 s[44:45], s[40:41]
	s_cbranch_execz .LBB0_874
	v_lshlrev_b64 v[2:3], 6, v[16:17]
	v_lshl_add_u64 v[2:3], s[20:21], 0, v[2:3]
	v_lshl_add_u64 v[2:3], s[34:35], 2, v[2:3]
	s_lshl_b32 s36, s27, 2
	v_lshl_add_u64 v[2:3], v[2:3], 0, s[36:37]
	s_waitcnt lgkmcnt(0)
	v_add_f32_e32 v0, v0, v1
	global_store_dword v[2:3], v0, off
